# RG-LRU scan: gate reads of the next 4-step group issued ahead (double-buffered, counted lgkmcnt), on top of lower-half static priority
# speedup vs baseline: 1.0018x; 1.0018x over previous
; DI bf16_t f2bf(float x) { unsigned u = __float_as_uint(x); u += 0x7fffu + ((u >> 16) & 1u); return (bf16_t)(u >> 16); }
; DI float bf2f(bf16_t b) { return __uint_as_float(((unsigned)b) << 16); }
; DI float sigmoidf_(float x) { return __builtin_amdgcn_rcpf(1.f + __expf(-x)); }
; template <bool PASS2>
; DI void lru_item(const Params& p, int l, int item, int lane, const bf16_t* xl, float* wxs) {
;     ...
;   for (int t = 0; t < LCL; t++) {
;     const float x0 = xn;
;     if (t + 1 < LCL) xn = bf2f(xl[(tok0 + t + 1) * 512 + ch]);
;     const float xc = cw3 * x0 + cw2 * x1 + cw1 * x2 + cw0 * x3 + cb;
;     x3 = x2; x2 = x1; x1 = x0;
;     float ra0 = ba, ra1 = 0.f, rx0 = bx, rx1 = 0.f;
;     const unsigned xb16 = (unsigned)f2bf(xc);
;     const unsigned xnb = (unsigned)__shfl_xor((int)xb16, 1);
;     const unsigned xpk = xb16 | (xnb << 16);
; #pragma unroll
;     for (int m = 0; m < 32; m += 2) {
;       const bf2_t xa = __builtin_bit_cast(bf2_t, (unsigned)__builtin_amdgcn_readlane((int)xpk, 2 * m));
;       const bf2_t xb = __builtin_bit_cast(bf2_t, (unsigned)__builtin_amdgcn_readlane((int)xpk, 2 * m + 2));
;       ra0 = __builtin_amdgcn_fdot2_f32_bf16(xa, __builtin_bit_cast(bf2_t, wpa[m]), ra0, false);
;       rx0 = __builtin_amdgcn_fdot2_f32_bf16(xa, __builtin_bit_cast(bf2_t, wpx[m]), rx0, false);
;       ra1 = __builtin_amdgcn_fdot2_f32_bf16(xb, __builtin_bit_cast(bf2_t, wpa[m + 1]), ra1, false);
;       rx1 = __builtin_amdgcn_fdot2_f32_bf16(xb, __builtin_bit_cast(bf2_t, wpx[m + 1]), rx1, false);
;     }
;     const float rg = sigmoidf_(ra0 + ra1), ig = sigmoidf_(rx0 + rx1);
;     const float la = -8.f * rg * sp;
;     const float a = __expf(la);
;     const float inp = sqrtf(fmaxf(1.f - a * a, 0.f)) * (ig * xc);
;     hs = a * hs + inp;
;     if (PASS2) p.yd[(tok0 + t) * 512 + ch] = f2bf(hs);
;     else aprod *= a;
.Llrua1_noload:
	ds_read_b32 v0, v77 offset:0
	ds_read_b32 v1, v77 offset:256
	ds_read_b32 v2, v77 offset:528
	ds_read_b32 v3, v77 offset:784
	ds_read_b32 v4, v77 offset:1056
	ds_read_b32 v5, v77 offset:1312
	ds_read_b32 v6, v77 offset:1584
	ds_read_b32 v7, v77 offset:1840
	ds_read_b32 v36, v77 offset:2112
	ds_read_b32 v37, v77 offset:2368
	ds_read_b32 v38, v77 offset:2640
	ds_read_b32 v39, v77 offset:2896
	ds_read_b32 v40, v77 offset:3168
	ds_read_b32 v41, v77 offset:3424
	ds_read_b32 v42, v77 offset:3696
	ds_read_b32 v43, v77 offset:3952
	s_waitcnt lgkmcnt(8)
	v_add_f32_e32 v0, v0, v13
	v_add_f32_e32 v1, v1, v14
	v_mul_f32_e32 v0, 0xbfb8aa3b, v0
	v_mul_f32_e32 v1, 0xbfb8aa3b, v1
	v_exp_f32_e32 v0, v0
	v_exp_f32_e32 v1, v1
	v_add_f32_e32 v0, 1.0, v0
	v_add_f32_e32 v1, 1.0, v1
	v_rcp_f32_e32 v0, v0
	v_rcp_f32_e32 v1, v1
	v_mul_f32_e32 v80, v0, v15
	v_exp_f32_e32 v80, v80
	v_mul_f32_e32 v147, v1, v52
	v_fma_f32 v146, -v80, v80, 1.0
	v_max_f32_e32 v146, 0, v146
	v_sqrt_f32_e32 v146, v146
	v_mul_f32_e32 v68, v68, v80
	v_mul_f32_e32 v147, v146, v147
	v_fma_f32 v19, v80, v19, v147
	v_add_f32_e32 v2, v2, v13
	v_add_f32_e32 v3, v3, v14
	v_mul_f32_e32 v2, 0xbfb8aa3b, v2
	v_mul_f32_e32 v3, 0xbfb8aa3b, v3
	v_exp_f32_e32 v2, v2
	v_exp_f32_e32 v3, v3
	v_add_f32_e32 v2, 1.0, v2
	v_add_f32_e32 v3, 1.0, v3
	v_rcp_f32_e32 v2, v2
	v_rcp_f32_e32 v3, v3
	v_mul_f32_e32 v80, v2, v15
	v_exp_f32_e32 v80, v80
	v_mul_f32_e32 v147, v3, v53
	v_fma_f32 v146, -v80, v80, 1.0
	v_max_f32_e32 v146, 0, v146
	v_sqrt_f32_e32 v146, v146
	v_mul_f32_e32 v68, v68, v80
	v_mul_f32_e32 v147, v146, v147
	v_fma_f32 v19, v80, v19, v147
	v_add_f32_e32 v4, v4, v13
	v_add_f32_e32 v5, v5, v14
	v_mul_f32_e32 v4, 0xbfb8aa3b, v4
	v_mul_f32_e32 v5, 0xbfb8aa3b, v5
	v_exp_f32_e32 v4, v4
	v_exp_f32_e32 v5, v5
	v_add_f32_e32 v4, 1.0, v4
	v_add_f32_e32 v5, 1.0, v5
	v_rcp_f32_e32 v4, v4
	v_rcp_f32_e32 v5, v5
	v_mul_f32_e32 v80, v4, v15
	v_exp_f32_e32 v80, v80
	v_mul_f32_e32 v147, v5, v54
	v_fma_f32 v146, -v80, v80, 1.0
	v_max_f32_e32 v146, 0, v146
	v_sqrt_f32_e32 v146, v146
	v_mul_f32_e32 v68, v68, v80
	v_mul_f32_e32 v147, v146, v147
	v_fma_f32 v19, v80, v19, v147
	v_add_f32_e32 v6, v6, v13
	v_add_f32_e32 v7, v7, v14
	v_mul_f32_e32 v6, 0xbfb8aa3b, v6
	v_mul_f32_e32 v7, 0xbfb8aa3b, v7
	v_exp_f32_e32 v6, v6
	v_exp_f32_e32 v7, v7
	v_add_f32_e32 v6, 1.0, v6
	v_add_f32_e32 v7, 1.0, v7
	v_rcp_f32_e32 v6, v6
	v_rcp_f32_e32 v7, v7
	v_mul_f32_e32 v80, v6, v15
	v_exp_f32_e32 v80, v80
	v_mul_f32_e32 v147, v7, v55
	v_fma_f32 v146, -v80, v80, 1.0
	v_max_f32_e32 v146, 0, v146
	v_sqrt_f32_e32 v146, v146
	v_mul_f32_e32 v68, v68, v80
	v_mul_f32_e32 v147, v146, v147
	v_fma_f32 v19, v80, v19, v147
	ds_read_b32 v0, v77 offset:4224
	ds_read_b32 v1, v77 offset:4480
	ds_read_b32 v2, v77 offset:4752
	ds_read_b32 v3, v77 offset:5008
	ds_read_b32 v4, v77 offset:5280
	ds_read_b32 v5, v77 offset:5536
	ds_read_b32 v6, v77 offset:5808
	ds_read_b32 v7, v77 offset:6064
	s_waitcnt lgkmcnt(8)
	v_add_f32_e32 v36, v36, v13
	v_add_f32_e32 v37, v37, v14
	v_mul_f32_e32 v36, 0xbfb8aa3b, v36
	v_mul_f32_e32 v37, 0xbfb8aa3b, v37
	v_exp_f32_e32 v36, v36
	v_exp_f32_e32 v37, v37
	v_add_f32_e32 v36, 1.0, v36
	v_add_f32_e32 v37, 1.0, v37
	v_rcp_f32_e32 v36, v36
	v_rcp_f32_e32 v37, v37
	v_mul_f32_e32 v80, v36, v15
	v_exp_f32_e32 v80, v80
	v_mul_f32_e32 v147, v37, v56
	v_fma_f32 v146, -v80, v80, 1.0
	v_max_f32_e32 v146, 0, v146
	v_sqrt_f32_e32 v146, v146
	v_mul_f32_e32 v68, v68, v80
	v_mul_f32_e32 v147, v146, v147
	v_fma_f32 v19, v80, v19, v147
	v_add_f32_e32 v38, v38, v13
	v_add_f32_e32 v39, v39, v14
	v_mul_f32_e32 v38, 0xbfb8aa3b, v38
	v_mul_f32_e32 v39, 0xbfb8aa3b, v39
	v_exp_f32_e32 v38, v38
	v_exp_f32_e32 v39, v39
	v_add_f32_e32 v38, 1.0, v38
	v_add_f32_e32 v39, 1.0, v39
	v_rcp_f32_e32 v38, v38
	v_rcp_f32_e32 v39, v39
	v_mul_f32_e32 v80, v38, v15
	v_exp_f32_e32 v80, v80
	v_mul_f32_e32 v147, v39, v57
	v_fma_f32 v146, -v80, v80, 1.0
	v_max_f32_e32 v146, 0, v146
	v_sqrt_f32_e32 v146, v146
	v_mul_f32_e32 v68, v68, v80
	v_mul_f32_e32 v147, v146, v147
	v_fma_f32 v19, v80, v19, v147
	v_add_f32_e32 v40, v40, v13
	v_add_f32_e32 v41, v41, v14
	v_mul_f32_e32 v40, 0xbfb8aa3b, v40
	v_mul_f32_e32 v41, 0xbfb8aa3b, v41
	v_exp_f32_e32 v40, v40
	v_exp_f32_e32 v41, v41
	v_add_f32_e32 v40, 1.0, v40
	v_add_f32_e32 v41, 1.0, v41
	v_rcp_f32_e32 v40, v40
	v_rcp_f32_e32 v41, v41
	v_mul_f32_e32 v80, v40, v15
	v_exp_f32_e32 v80, v80
	v_mul_f32_e32 v147, v41, v58
	v_fma_f32 v146, -v80, v80, 1.0
	v_max_f32_e32 v146, 0, v146
	v_sqrt_f32_e32 v146, v146
	v_mul_f32_e32 v68, v68, v80
	v_mul_f32_e32 v147, v146, v147
	v_fma_f32 v19, v80, v19, v147
	v_add_f32_e32 v42, v42, v13
	v_add_f32_e32 v43, v43, v14
	v_mul_f32_e32 v42, 0xbfb8aa3b, v42
	v_mul_f32_e32 v43, 0xbfb8aa3b, v43
	v_exp_f32_e32 v42, v42
	v_exp_f32_e32 v43, v43
	v_add_f32_e32 v42, 1.0, v42
	v_add_f32_e32 v43, 1.0, v43
	v_rcp_f32_e32 v42, v42
	v_rcp_f32_e32 v43, v43
	v_mul_f32_e32 v80, v42, v15
	v_exp_f32_e32 v80, v80
	v_mul_f32_e32 v147, v43, v59
	v_fma_f32 v146, -v80, v80, 1.0
	v_max_f32_e32 v146, 0, v146
	v_sqrt_f32_e32 v146, v146
	v_mul_f32_e32 v68, v68, v80
	v_mul_f32_e32 v147, v146, v147
	v_fma_f32 v19, v80, v19, v147
	ds_read_b32 v36, v77 offset:6336
	ds_read_b32 v37, v77 offset:6592
	ds_read_b32 v38, v77 offset:6864
	ds_read_b32 v39, v77 offset:7120
	ds_read_b32 v40, v77 offset:7392
	ds_read_b32 v41, v77 offset:7648
	ds_read_b32 v42, v77 offset:7920
	ds_read_b32 v43, v77 offset:8176
	s_waitcnt lgkmcnt(8)
; DI bf16_t f2bf(float x) { unsigned u = __float_as_uint(x); u += 0x7fffu + ((u >> 16) & 1u); return (bf16_t)(u >> 16); }
; DI float sigmoidf_(float x) { return __builtin_amdgcn_rcpf(1.f + __expf(-x)); }
; template <bool PASS2>
; DI void lru_item(const Params& p, int l, int item, int lane, const bf16_t* xl, float* wxs) {
;     ...
;     const float rg = sigmoidf_(ra0 + ra1), ig = sigmoidf_(rx0 + rx1);
;     const float la = -8.f * rg * sp;
;     const float a = __expf(la);
;     const float inp = sqrtf(fmaxf(1.f - a * a, 0.f)) * (ig * xc);
;     hs = a * hs + inp;
;     if (PASS2) p.yd[(tok0 + t) * 512 + ch] = f2bf(hs);
;     else aprod *= a;
;   }
;   if (!PASS2) { st[0] = aprod; st[1] = hs; }
	v_add_f32_e32 v0, v0, v13
	v_add_f32_e32 v1, v1, v14
	v_mul_f32_e32 v0, 0xbfb8aa3b, v0
	v_mul_f32_e32 v1, 0xbfb8aa3b, v1
	v_exp_f32_e32 v0, v0
	v_exp_f32_e32 v1, v1
	v_add_f32_e32 v0, 1.0, v0
	v_add_f32_e32 v1, 1.0, v1
	v_rcp_f32_e32 v0, v0
	v_rcp_f32_e32 v1, v1
	v_mul_f32_e32 v80, v0, v15
	v_exp_f32_e32 v80, v80
	v_mul_f32_e32 v147, v1, v60
	v_fma_f32 v146, -v80, v80, 1.0
	v_max_f32_e32 v146, 0, v146
	v_sqrt_f32_e32 v146, v146
	v_mul_f32_e32 v68, v68, v80
	v_mul_f32_e32 v147, v146, v147
	v_fma_f32 v19, v80, v19, v147
	v_add_f32_e32 v2, v2, v13
	v_add_f32_e32 v3, v3, v14
	v_mul_f32_e32 v2, 0xbfb8aa3b, v2
	v_mul_f32_e32 v3, 0xbfb8aa3b, v3
	v_exp_f32_e32 v2, v2
	v_exp_f32_e32 v3, v3
	v_add_f32_e32 v2, 1.0, v2
	v_add_f32_e32 v3, 1.0, v3
	v_rcp_f32_e32 v2, v2
	v_rcp_f32_e32 v3, v3
	v_mul_f32_e32 v80, v2, v15
	v_exp_f32_e32 v80, v80
	v_mul_f32_e32 v147, v3, v61
	v_fma_f32 v146, -v80, v80, 1.0
	v_max_f32_e32 v146, 0, v146
	v_sqrt_f32_e32 v146, v146
	v_mul_f32_e32 v68, v68, v80
	v_mul_f32_e32 v147, v146, v147
	v_fma_f32 v19, v80, v19, v147
	v_add_f32_e32 v4, v4, v13
	v_add_f32_e32 v5, v5, v14
	v_mul_f32_e32 v4, 0xbfb8aa3b, v4
	v_mul_f32_e32 v5, 0xbfb8aa3b, v5
	v_exp_f32_e32 v4, v4
	v_exp_f32_e32 v5, v5
	v_add_f32_e32 v4, 1.0, v4
	v_add_f32_e32 v5, 1.0, v5
	v_rcp_f32_e32 v4, v4
	v_rcp_f32_e32 v5, v5
	v_mul_f32_e32 v80, v4, v15
	v_exp_f32_e32 v80, v80
	v_mul_f32_e32 v147, v5, v62
	v_fma_f32 v146, -v80, v80, 1.0
	v_max_f32_e32 v146, 0, v146
	v_sqrt_f32_e32 v146, v146
	v_mul_f32_e32 v68, v68, v80
	v_mul_f32_e32 v147, v146, v147
	v_fma_f32 v19, v80, v19, v147
	v_add_f32_e32 v6, v6, v13
	v_add_f32_e32 v7, v7, v14
	v_mul_f32_e32 v6, 0xbfb8aa3b, v6
	v_mul_f32_e32 v7, 0xbfb8aa3b, v7
	v_exp_f32_e32 v6, v6
	v_exp_f32_e32 v7, v7
	v_add_f32_e32 v6, 1.0, v6
	v_add_f32_e32 v7, 1.0, v7
	v_rcp_f32_e32 v6, v6
	v_rcp_f32_e32 v7, v7
	v_mul_f32_e32 v80, v6, v15
	v_exp_f32_e32 v80, v80
	v_mul_f32_e32 v147, v7, v63
	v_fma_f32 v146, -v80, v80, 1.0
	v_max_f32_e32 v146, 0, v146
	v_sqrt_f32_e32 v146, v146
	v_mul_f32_e32 v68, v68, v80
	v_mul_f32_e32 v147, v146, v147
	v_fma_f32 v19, v80, v19, v147
	s_waitcnt lgkmcnt(0)
	v_add_f32_e32 v36, v36, v13
	v_add_f32_e32 v37, v37, v14
	v_mul_f32_e32 v36, 0xbfb8aa3b, v36
	v_mul_f32_e32 v37, 0xbfb8aa3b, v37
	v_exp_f32_e32 v36, v36
	v_exp_f32_e32 v37, v37
	v_add_f32_e32 v36, 1.0, v36
	v_add_f32_e32 v37, 1.0, v37
	v_rcp_f32_e32 v36, v36
	v_rcp_f32_e32 v37, v37
	v_mul_f32_e32 v80, v36, v15
	v_exp_f32_e32 v80, v80
	v_mul_f32_e32 v147, v37, v64
	v_fma_f32 v146, -v80, v80, 1.0
	v_max_f32_e32 v146, 0, v146
	v_sqrt_f32_e32 v146, v146
	v_mul_f32_e32 v68, v68, v80
	v_mul_f32_e32 v147, v146, v147
	v_fma_f32 v19, v80, v19, v147
	v_add_f32_e32 v38, v38, v13
	v_add_f32_e32 v39, v39, v14
	v_mul_f32_e32 v38, 0xbfb8aa3b, v38
	v_mul_f32_e32 v39, 0xbfb8aa3b, v39
	v_exp_f32_e32 v38, v38
	v_exp_f32_e32 v39, v39
	v_add_f32_e32 v38, 1.0, v38
	v_add_f32_e32 v39, 1.0, v39
	v_rcp_f32_e32 v38, v38
	v_rcp_f32_e32 v39, v39
	v_mul_f32_e32 v80, v38, v15
	v_exp_f32_e32 v80, v80
	v_mul_f32_e32 v147, v39, v65
	v_fma_f32 v146, -v80, v80, 1.0
	v_max_f32_e32 v146, 0, v146
	v_sqrt_f32_e32 v146, v146
	v_mul_f32_e32 v68, v68, v80
	v_mul_f32_e32 v147, v146, v147
	v_fma_f32 v19, v80, v19, v147
	v_add_f32_e32 v40, v40, v13
	v_add_f32_e32 v41, v41, v14
	v_mul_f32_e32 v40, 0xbfb8aa3b, v40
	v_mul_f32_e32 v41, 0xbfb8aa3b, v41
	v_exp_f32_e32 v40, v40
	v_exp_f32_e32 v41, v41
	v_add_f32_e32 v40, 1.0, v40
	v_add_f32_e32 v41, 1.0, v41
	v_rcp_f32_e32 v40, v40
	v_rcp_f32_e32 v41, v41
	v_mul_f32_e32 v80, v40, v15
	v_exp_f32_e32 v80, v80
	v_mul_f32_e32 v147, v41, v66
	v_fma_f32 v146, -v80, v80, 1.0
	v_max_f32_e32 v146, 0, v146
	v_sqrt_f32_e32 v146, v146
	v_mul_f32_e32 v68, v68, v80
	v_mul_f32_e32 v147, v146, v147
	v_fma_f32 v19, v80, v19, v147
	v_add_f32_e32 v42, v42, v13
	v_add_f32_e32 v43, v43, v14
	v_mul_f32_e32 v42, 0xbfb8aa3b, v42
	v_mul_f32_e32 v43, 0xbfb8aa3b, v43
	v_exp_f32_e32 v42, v42
	v_exp_f32_e32 v43, v43
	v_add_f32_e32 v42, 1.0, v42
	v_add_f32_e32 v43, 1.0, v43
	v_rcp_f32_e32 v42, v42
	v_rcp_f32_e32 v43, v43
	v_mul_f32_e32 v80, v42, v15
	v_exp_f32_e32 v80, v80
	v_mul_f32_e32 v147, v43, v67
	v_fma_f32 v146, -v80, v80, 1.0
	v_max_f32_e32 v146, 0, v146
	v_sqrt_f32_e32 v146, v146
	v_mul_f32_e32 v68, v68, v80
	v_mul_f32_e32 v147, v146, v147
	v_fma_f32 v19, v80, v19, v147
	s_add_u32 s20, s20, 1
	s_waitcnt vmcnt(0)
	s_cmp_lt_u32 s20, 8
	s_cbranch_scc1 .Llrua1_loop
	v_and_b32_e32 v78, 63, v210
	s_bfe_u32 s16, s12, 0x30007
	v_lshl_add_u32 v78, s16, 6, v78
	v_lshl_add_u32 v78, s19, 9, v78
	v_lshlrev_b32_e32 v78, 7, v78
	v_add_u32_e32 v78, s17, v78
	v_lshlrev_b32_e32 v78, 3, v78
	s_add_u32 s0, s2, 0x3158000
	s_addc_u32 s1, s3, 0
	global_store_dword v78, v68, s[0:1]
	global_store_dword v78, v19, s[0:1] offset:4
	s_waitcnt vmcnt(0)
	s_add_u32 s12, s12, s13
	s_cmpk_lt_i32 s12, 0x800
	s_cbranch_scc1 .Llrua1_item

; DI bf16_t f2bf(float x) { unsigned u = __float_as_uint(x); u += 0x7fffu + ((u >> 16) & 1u); return (bf16_t)(u >> 16); }
; DI float sigmoidf_(float x) { return __builtin_amdgcn_rcpf(1.f + __expf(-x)); }
; template <bool PASS2>
; DI void lru_item(const Params& p, int l, int item, int lane, const bf16_t* xl, float* wxs) {
;     ...
;     const float rg = sigmoidf_(ra0 + ra1), ig = sigmoidf_(rx0 + rx1);
;     const float la = -8.f * rg * sp;
;     const float a = __expf(la);
;     const float inp = sqrtf(fmaxf(1.f - a * a, 0.f)) * (ig * xc);
;     hs = a * hs + inp;
;     if (PASS2) p.yd[(tok0 + t) * 512 + ch] = f2bf(hs);
.Llrua2_noload:
	ds_read_b32 v0, v109 offset:0
	ds_read_b32 v1, v109 offset:256
	ds_read_b32 v2, v109 offset:528
	ds_read_b32 v3, v109 offset:784
	ds_read_b32 v4, v109 offset:1056
	ds_read_b32 v5, v109 offset:1312
	ds_read_b32 v6, v109 offset:1584
	ds_read_b32 v7, v109 offset:1840
	ds_read_b32 v130, v109 offset:2112
	ds_read_b32 v131, v109 offset:2368
	ds_read_b32 v132, v109 offset:2640
	ds_read_b32 v133, v109 offset:2896
	ds_read_b32 v134, v109 offset:3168
	ds_read_b32 v135, v109 offset:3424
	ds_read_b32 v136, v109 offset:3696
	ds_read_b32 v137, v109 offset:3952
	s_waitcnt lgkmcnt(8)
	v_add_f32_e32 v0, v0, v13
	v_add_f32_e32 v1, v1, v14
	v_mul_f32_e32 v0, 0xbfb8aa3b, v0
	v_mul_f32_e32 v1, 0xbfb8aa3b, v1
	v_exp_f32_e32 v0, v0
	v_exp_f32_e32 v1, v1
	v_add_f32_e32 v0, 1.0, v0
	v_add_f32_e32 v1, 1.0, v1
	v_rcp_f32_e32 v0, v0
	v_rcp_f32_e32 v1, v1
	v_mul_f32_e32 v112, v0, v15
	v_exp_f32_e32 v112, v112
	v_mul_f32_e32 v147, v1, v88
	v_fma_f32 v146, -v112, v112, 1.0
	v_max_f32_e32 v146, 0, v146
	v_sqrt_f32_e32 v146, v146
	s_nop 0
	v_mul_f32_e32 v147, v146, v147
	v_fma_f32 v16, v112, v16, v147
	v_bfe_u32 v146, v16, 16, 1
	v_add3_u32 v146, v16, v146, s1
	global_store_short_d16_hi v17, v146, s[10:11] offset:0
	v_add_f32_e32 v2, v2, v13
	v_add_f32_e32 v3, v3, v14
	v_mul_f32_e32 v2, 0xbfb8aa3b, v2
	v_mul_f32_e32 v3, 0xbfb8aa3b, v3
	v_exp_f32_e32 v2, v2
	v_exp_f32_e32 v3, v3
	v_add_f32_e32 v2, 1.0, v2
	v_add_f32_e32 v3, 1.0, v3
	v_rcp_f32_e32 v2, v2
	v_rcp_f32_e32 v3, v3
	v_mul_f32_e32 v112, v2, v15
	v_exp_f32_e32 v112, v112
	v_mul_f32_e32 v147, v3, v89
	v_fma_f32 v146, -v112, v112, 1.0
	v_max_f32_e32 v146, 0, v146
	v_sqrt_f32_e32 v146, v146
	s_nop 0
	v_mul_f32_e32 v147, v146, v147
	v_fma_f32 v16, v112, v16, v147
	v_bfe_u32 v146, v16, 16, 1
	v_add3_u32 v146, v16, v146, s1
	global_store_short_d16_hi v17, v146, s[10:11] offset:1024
	v_add_f32_e32 v4, v4, v13
	v_add_f32_e32 v5, v5, v14
	v_mul_f32_e32 v4, 0xbfb8aa3b, v4
	v_mul_f32_e32 v5, 0xbfb8aa3b, v5
	v_exp_f32_e32 v4, v4
	v_exp_f32_e32 v5, v5
	v_add_f32_e32 v4, 1.0, v4
	v_add_f32_e32 v5, 1.0, v5
	v_rcp_f32_e32 v4, v4
	v_rcp_f32_e32 v5, v5
	v_mul_f32_e32 v112, v4, v15
	v_exp_f32_e32 v112, v112
	v_mul_f32_e32 v147, v5, v90
	v_fma_f32 v146, -v112, v112, 1.0
	v_max_f32_e32 v146, 0, v146
	v_sqrt_f32_e32 v146, v146
	s_nop 0
	v_mul_f32_e32 v147, v146, v147
	v_fma_f32 v16, v112, v16, v147
	v_bfe_u32 v146, v16, 16, 1
	v_add3_u32 v146, v16, v146, s1
	global_store_short_d16_hi v17, v146, s[10:11] offset:2048
	v_add_f32_e32 v6, v6, v13
	v_add_f32_e32 v7, v7, v14
	v_mul_f32_e32 v6, 0xbfb8aa3b, v6
	v_mul_f32_e32 v7, 0xbfb8aa3b, v7
	v_exp_f32_e32 v6, v6
	v_exp_f32_e32 v7, v7
	v_add_f32_e32 v6, 1.0, v6
	v_add_f32_e32 v7, 1.0, v7
	v_rcp_f32_e32 v6, v6
	v_rcp_f32_e32 v7, v7
	v_mul_f32_e32 v112, v6, v15
	v_exp_f32_e32 v112, v112
	v_mul_f32_e32 v147, v7, v91
	v_fma_f32 v146, -v112, v112, 1.0
	v_max_f32_e32 v146, 0, v146
	v_sqrt_f32_e32 v146, v146
	s_nop 0
	v_mul_f32_e32 v147, v146, v147
	v_fma_f32 v16, v112, v16, v147
	v_bfe_u32 v146, v16, 16, 1
	v_add3_u32 v146, v16, v146, s1
	global_store_short_d16_hi v17, v146, s[10:11] offset:3072
	v_add_u32_e32 v17, 0x1000, v17
	ds_read_b32 v0, v109 offset:4224
	ds_read_b32 v1, v109 offset:4480
	ds_read_b32 v2, v109 offset:4752
	ds_read_b32 v3, v109 offset:5008
	ds_read_b32 v4, v109 offset:5280
	ds_read_b32 v5, v109 offset:5536
	ds_read_b32 v6, v109 offset:5808
	ds_read_b32 v7, v109 offset:6064
	s_waitcnt lgkmcnt(8)
	v_add_f32_e32 v130, v130, v13
	v_add_f32_e32 v131, v131, v14
	v_mul_f32_e32 v130, 0xbfb8aa3b, v130
	v_mul_f32_e32 v131, 0xbfb8aa3b, v131
	v_exp_f32_e32 v130, v130
	v_exp_f32_e32 v131, v131
	v_add_f32_e32 v130, 1.0, v130
	v_add_f32_e32 v131, 1.0, v131
	v_rcp_f32_e32 v130, v130
	v_rcp_f32_e32 v131, v131
	v_mul_f32_e32 v112, v130, v15
	v_exp_f32_e32 v112, v112
	v_mul_f32_e32 v147, v131, v92
	v_fma_f32 v146, -v112, v112, 1.0
	v_max_f32_e32 v146, 0, v146
	v_sqrt_f32_e32 v146, v146
	s_nop 0
	v_mul_f32_e32 v147, v146, v147
	v_fma_f32 v16, v112, v16, v147
	v_bfe_u32 v146, v16, 16, 1
	v_add3_u32 v146, v16, v146, s1
	global_store_short_d16_hi v17, v146, s[10:11] offset:0
	v_add_f32_e32 v132, v132, v13
	v_add_f32_e32 v133, v133, v14
	v_mul_f32_e32 v132, 0xbfb8aa3b, v132
	v_mul_f32_e32 v133, 0xbfb8aa3b, v133
	v_exp_f32_e32 v132, v132
	v_exp_f32_e32 v133, v133
	v_add_f32_e32 v132, 1.0, v132
	v_add_f32_e32 v133, 1.0, v133
	v_rcp_f32_e32 v132, v132
	v_rcp_f32_e32 v133, v133
	v_mul_f32_e32 v112, v132, v15
	v_exp_f32_e32 v112, v112
	v_mul_f32_e32 v147, v133, v93
	v_fma_f32 v146, -v112, v112, 1.0
	v_max_f32_e32 v146, 0, v146
	v_sqrt_f32_e32 v146, v146
	s_nop 0
	v_mul_f32_e32 v147, v146, v147
	v_fma_f32 v16, v112, v16, v147
	v_bfe_u32 v146, v16, 16, 1
	v_add3_u32 v146, v16, v146, s1
	global_store_short_d16_hi v17, v146, s[10:11] offset:1024
	v_add_f32_e32 v134, v134, v13
	v_add_f32_e32 v135, v135, v14
	v_mul_f32_e32 v134, 0xbfb8aa3b, v134
	v_mul_f32_e32 v135, 0xbfb8aa3b, v135
	v_exp_f32_e32 v134, v134
	v_exp_f32_e32 v135, v135
	v_add_f32_e32 v134, 1.0, v134
	v_add_f32_e32 v135, 1.0, v135
	v_rcp_f32_e32 v134, v134
	v_rcp_f32_e32 v135, v135
	v_mul_f32_e32 v112, v134, v15
	v_exp_f32_e32 v112, v112
	v_mul_f32_e32 v147, v135, v94
	v_fma_f32 v146, -v112, v112, 1.0
	v_max_f32_e32 v146, 0, v146
	v_sqrt_f32_e32 v146, v146
	s_nop 0
	v_mul_f32_e32 v147, v146, v147
	v_fma_f32 v16, v112, v16, v147
	v_bfe_u32 v146, v16, 16, 1
	v_add3_u32 v146, v16, v146, s1
	global_store_short_d16_hi v17, v146, s[10:11] offset:2048
	v_add_f32_e32 v136, v136, v13
	v_add_f32_e32 v137, v137, v14
	v_mul_f32_e32 v136, 0xbfb8aa3b, v136
	v_mul_f32_e32 v137, 0xbfb8aa3b, v137
	v_exp_f32_e32 v136, v136
	v_exp_f32_e32 v137, v137
	v_add_f32_e32 v136, 1.0, v136
	v_add_f32_e32 v137, 1.0, v137
	v_rcp_f32_e32 v136, v136
	v_rcp_f32_e32 v137, v137
	v_mul_f32_e32 v112, v136, v15
	v_exp_f32_e32 v112, v112
	v_mul_f32_e32 v147, v137, v95
	v_fma_f32 v146, -v112, v112, 1.0
	v_max_f32_e32 v146, 0, v146
	v_sqrt_f32_e32 v146, v146
	s_nop 0
	v_mul_f32_e32 v147, v146, v147
	v_fma_f32 v16, v112, v16, v147
	v_bfe_u32 v146, v16, 16, 1
	v_add3_u32 v146, v16, v146, s1
	global_store_short_d16_hi v17, v146, s[10:11] offset:3072
	v_add_u32_e32 v17, 0x1000, v17
	ds_read_b32 v130, v109 offset:6336
	ds_read_b32 v131, v109 offset:6592
	ds_read_b32 v132, v109 offset:6864
	ds_read_b32 v133, v109 offset:7120
	ds_read_b32 v134, v109 offset:7392
	ds_read_b32 v135, v109 offset:7648
	ds_read_b32 v136, v109 offset:7920
	ds_read_b32 v137, v109 offset:8176
	s_waitcnt lgkmcnt(8)
; DI bf16_t f2bf(float x) { unsigned u = __float_as_uint(x); u += 0x7fffu + ((u >> 16) & 1u); return (bf16_t)(u >> 16); }
; DI float sigmoidf_(float x) { return __builtin_amdgcn_rcpf(1.f + __expf(-x)); }
; template <bool PASS2>
; DI void lru_item(const Params& p, int l, int item, int lane, const bf16_t* xl, float* wxs) {
;     ...
;     const float rg = sigmoidf_(ra0 + ra1), ig = sigmoidf_(rx0 + rx1);
;     const float la = -8.f * rg * sp;
;     const float a = __expf(la);
;     const float inp = sqrtf(fmaxf(1.f - a * a, 0.f)) * (ig * xc);
;     hs = a * hs + inp;
;     if (PASS2) p.yd[(tok0 + t) * 512 + ch] = f2bf(hs);
	v_add_f32_e32 v0, v0, v13
	v_add_f32_e32 v1, v1, v14
	v_mul_f32_e32 v0, 0xbfb8aa3b, v0
	v_mul_f32_e32 v1, 0xbfb8aa3b, v1
	v_exp_f32_e32 v0, v0
	v_exp_f32_e32 v1, v1
	v_add_f32_e32 v0, 1.0, v0
	v_add_f32_e32 v1, 1.0, v1
	v_rcp_f32_e32 v0, v0
	v_rcp_f32_e32 v1, v1
	v_mul_f32_e32 v112, v0, v15
	v_exp_f32_e32 v112, v112
	v_mul_f32_e32 v147, v1, v96
	v_fma_f32 v146, -v112, v112, 1.0
	v_max_f32_e32 v146, 0, v146
	v_sqrt_f32_e32 v146, v146
	s_nop 0
	v_mul_f32_e32 v147, v146, v147
	v_fma_f32 v16, v112, v16, v147
	v_bfe_u32 v146, v16, 16, 1
	v_add3_u32 v146, v16, v146, s1
	global_store_short_d16_hi v17, v146, s[10:11] offset:0
	v_add_f32_e32 v2, v2, v13
	v_add_f32_e32 v3, v3, v14
	v_mul_f32_e32 v2, 0xbfb8aa3b, v2
	v_mul_f32_e32 v3, 0xbfb8aa3b, v3
	v_exp_f32_e32 v2, v2
	v_exp_f32_e32 v3, v3
	v_add_f32_e32 v2, 1.0, v2
	v_add_f32_e32 v3, 1.0, v3
	v_rcp_f32_e32 v2, v2
	v_rcp_f32_e32 v3, v3
	v_mul_f32_e32 v112, v2, v15
	v_exp_f32_e32 v112, v112
	v_mul_f32_e32 v147, v3, v97
	v_fma_f32 v146, -v112, v112, 1.0
	v_max_f32_e32 v146, 0, v146
	v_sqrt_f32_e32 v146, v146
	s_nop 0
	v_mul_f32_e32 v147, v146, v147
	v_fma_f32 v16, v112, v16, v147
	v_bfe_u32 v146, v16, 16, 1
	v_add3_u32 v146, v16, v146, s1
	global_store_short_d16_hi v17, v146, s[10:11] offset:1024
	v_add_f32_e32 v4, v4, v13
	v_add_f32_e32 v5, v5, v14
	v_mul_f32_e32 v4, 0xbfb8aa3b, v4
	v_mul_f32_e32 v5, 0xbfb8aa3b, v5
	v_exp_f32_e32 v4, v4
	v_exp_f32_e32 v5, v5
	v_add_f32_e32 v4, 1.0, v4
	v_add_f32_e32 v5, 1.0, v5
	v_rcp_f32_e32 v4, v4
	v_rcp_f32_e32 v5, v5
	v_mul_f32_e32 v112, v4, v15
	v_exp_f32_e32 v112, v112
	v_mul_f32_e32 v147, v5, v98
	v_fma_f32 v146, -v112, v112, 1.0
	v_max_f32_e32 v146, 0, v146
	v_sqrt_f32_e32 v146, v146
	s_nop 0
	v_mul_f32_e32 v147, v146, v147
	v_fma_f32 v16, v112, v16, v147
	v_bfe_u32 v146, v16, 16, 1
	v_add3_u32 v146, v16, v146, s1
	global_store_short_d16_hi v17, v146, s[10:11] offset:2048
	v_add_f32_e32 v6, v6, v13
	v_add_f32_e32 v7, v7, v14
	v_mul_f32_e32 v6, 0xbfb8aa3b, v6
	v_mul_f32_e32 v7, 0xbfb8aa3b, v7
	v_exp_f32_e32 v6, v6
	v_exp_f32_e32 v7, v7
	v_add_f32_e32 v6, 1.0, v6
	v_add_f32_e32 v7, 1.0, v7
	v_rcp_f32_e32 v6, v6
	v_rcp_f32_e32 v7, v7
	v_mul_f32_e32 v112, v6, v15
	v_exp_f32_e32 v112, v112
	v_mul_f32_e32 v147, v7, v99
	v_fma_f32 v146, -v112, v112, 1.0
	v_max_f32_e32 v146, 0, v146
	v_sqrt_f32_e32 v146, v146
	s_nop 0
	v_mul_f32_e32 v147, v146, v147
	v_fma_f32 v16, v112, v16, v147
	v_bfe_u32 v146, v16, 16, 1
	v_add3_u32 v146, v16, v146, s1
	global_store_short_d16_hi v17, v146, s[10:11] offset:3072
	v_add_u32_e32 v17, 0x1000, v17
	s_waitcnt lgkmcnt(0)
	v_add_f32_e32 v130, v130, v13
	v_add_f32_e32 v131, v131, v14
	v_mul_f32_e32 v130, 0xbfb8aa3b, v130
	v_mul_f32_e32 v131, 0xbfb8aa3b, v131
	v_exp_f32_e32 v130, v130
	v_exp_f32_e32 v131, v131
	v_add_f32_e32 v130, 1.0, v130
	v_add_f32_e32 v131, 1.0, v131
	v_rcp_f32_e32 v130, v130
	v_rcp_f32_e32 v131, v131
	v_mul_f32_e32 v112, v130, v15
	v_exp_f32_e32 v112, v112
	v_mul_f32_e32 v147, v131, v100
	v_fma_f32 v146, -v112, v112, 1.0
	v_max_f32_e32 v146, 0, v146
	v_sqrt_f32_e32 v146, v146
	s_nop 0
	v_mul_f32_e32 v147, v146, v147
	v_fma_f32 v16, v112, v16, v147
	v_bfe_u32 v146, v16, 16, 1
	v_add3_u32 v146, v16, v146, s1
	global_store_short_d16_hi v17, v146, s[10:11] offset:0
	v_add_f32_e32 v132, v132, v13
	v_add_f32_e32 v133, v133, v14
	v_mul_f32_e32 v132, 0xbfb8aa3b, v132
	v_mul_f32_e32 v133, 0xbfb8aa3b, v133
	v_exp_f32_e32 v132, v132
	v_exp_f32_e32 v133, v133
	v_add_f32_e32 v132, 1.0, v132
	v_add_f32_e32 v133, 1.0, v133
	v_rcp_f32_e32 v132, v132
	v_rcp_f32_e32 v133, v133
	v_mul_f32_e32 v112, v132, v15
	v_exp_f32_e32 v112, v112
	v_mul_f32_e32 v147, v133, v101
	v_fma_f32 v146, -v112, v112, 1.0
	v_max_f32_e32 v146, 0, v146
	v_sqrt_f32_e32 v146, v146
	s_nop 0
	v_mul_f32_e32 v147, v146, v147
	v_fma_f32 v16, v112, v16, v147
	v_bfe_u32 v146, v16, 16, 1
	v_add3_u32 v146, v16, v146, s1
	global_store_short_d16_hi v17, v146, s[10:11] offset:1024
	v_add_f32_e32 v134, v134, v13
	v_add_f32_e32 v135, v135, v14
	v_mul_f32_e32 v134, 0xbfb8aa3b, v134
	v_mul_f32_e32 v135, 0xbfb8aa3b, v135
	v_exp_f32_e32 v134, v134
	v_exp_f32_e32 v135, v135
	v_add_f32_e32 v134, 1.0, v134
	v_add_f32_e32 v135, 1.0, v135
	v_rcp_f32_e32 v134, v134
	v_rcp_f32_e32 v135, v135
	v_mul_f32_e32 v112, v134, v15
	v_exp_f32_e32 v112, v112
	v_mul_f32_e32 v147, v135, v102
	v_fma_f32 v146, -v112, v112, 1.0
	v_max_f32_e32 v146, 0, v146
	v_sqrt_f32_e32 v146, v146
	s_nop 0
	v_mul_f32_e32 v147, v146, v147
	v_fma_f32 v16, v112, v16, v147
	v_bfe_u32 v146, v16, 16, 1
	v_add3_u32 v146, v16, v146, s1
	global_store_short_d16_hi v17, v146, s[10:11] offset:2048
	v_add_f32_e32 v136, v136, v13
	v_add_f32_e32 v137, v137, v14
	v_mul_f32_e32 v136, 0xbfb8aa3b, v136
	v_mul_f32_e32 v137, 0xbfb8aa3b, v137
	v_exp_f32_e32 v136, v136
	v_exp_f32_e32 v137, v137
	v_add_f32_e32 v136, 1.0, v136
	v_add_f32_e32 v137, 1.0, v137
	v_rcp_f32_e32 v136, v136
	v_rcp_f32_e32 v137, v137
	v_mul_f32_e32 v112, v136, v15
	v_exp_f32_e32 v112, v112
	v_mul_f32_e32 v147, v137, v103
	v_fma_f32 v146, -v112, v112, 1.0
	v_max_f32_e32 v146, 0, v146
	v_sqrt_f32_e32 v146, v146
	s_nop 0
	v_mul_f32_e32 v147, v146, v147
	v_fma_f32 v16, v112, v16, v147
	v_bfe_u32 v146, v16, 16, 1
	v_add3_u32 v146, v16, v146, s1
	global_store_short_d16_hi v17, v146, s[10:11] offset:3072
	v_add_u32_e32 v17, 0x1000, v17
	s_add_u32 s20, s20, 1
	s_waitcnt vmcnt(16)
	s_cmp_lt_u32 s20, 8
	s_cbranch_scc1 .Llrua2_loop
	s_waitcnt vmcnt(0)
	s_add_u32 s12, s12, s13
	s_cmpk_lt_i32 s12, 0x800
	s_cbranch_scc1 .Llrua2_item
